# baseline (speedup 1.0000x reference)
; #define LAS __attribute__((address_space(3)))
; __global__ void __launch_bounds__(512, 2) fwd_megakernel(Params p) {
;   extern __shared__ __attribute__((aligned(16))) char lds[];
;   cg::grid_group grid = cg::this_grid();
;   unsigned* bar = (unsigned*)(p.ws + OFF_BAR);
;   volatile LAS unsigned* st = (volatile LAS unsigned*)(lds + LDS_BYTES);
;   {
;     const unsigned slot = (unsigned)__builtin_amdgcn_s_getreg((5 << 11) | 4) & 63u;
;     if ((threadIdx.x & 63) == 0) *(volatile __attribute__((address_space(3))) int*)(size_t)(WTBL_OFF + slot * 4) = (int)(threadIdx.x >> 6);
;     if (threadIdx.x == 0) { st[0] = 0u; st[1] = 0u; }
;     __syncthreads();
;   }
_Z14fwd_megakernel6Params:
	v_readfirstlane_b32 s100, v0
	s_nop 3
	s_bfe_u32 s100, s100, 0x40006
	s_nop 0
	v_writelane_b32 v255, s100, 63
	s_load_dword s14, s[0:1], 0xa8
	s_load_dwordx2 s[16:17], s[0:1], 0xa0
	s_mov_b32 s74, s2
	s_add_u32 s2, s0, 0xa0
	s_addc_u32 s3, s1, 0
	v_and_b32_e32 v1, 63, v0
	v_writelane_b32 v252, s2, 0
	s_getreg_b32 s4, hwreg(HW_REG_HW_ID, 0, 6)
	v_and_b32_e32 v6, 0x3ff, v0
	v_writelane_b32 v252, s3, 1
	v_cmp_eq_u32_e32 vcc, 0, v1
	s_and_saveexec_b64 s[2:3], vcc
	s_cbranch_execz .LBB0_2
	s_lshl_b32 s4, s4, 2
	s_and_b32 s4, s4, 0xfc
	s_add_i32 s4, s4, 0x20040
	v_lshrrev_b32_e32 v1, 6, v6
	v_mov_b32_e32 v2, s4
	ds_write_b32 v2, v1

; DI int my_tid() { int t = tid_raw(); asm volatile("" : "+v"(t)); return t; }
; DI int my_bid() { int b = blockIdx.x; asm volatile("" : "+s"(b)); return b; }
; DI void prologue(const Params& p, int layer, char* lds_all) {
;   unsigned char* ws = p.ws;
;   const int hb = my_tid() >> 8;
;   char* lds = lds_all + hb * HALF_LDS;
;   {
;     const int tid = my_tid() & 255;
;     int t2 = my_bid();
;     f32x4 cur[4], nxt[4];
;     WTile tc = wtile_of(p, ws, layer, (t2 < 2176 ? t2 : 0) * 2 + hb);
;     if (t2 < 2176) wtile_load(tc, tid, cur);
;     while (t2 < 2176) {
;       const int t2n = t2 + gridDim.x;
;       const WTile tn = wtile_of(p, ws, layer, (t2n < 2176 ? t2n : 0) * 2 + hb);
;       if (t2n < 2176) wtile_load(tn, tid, nxt);
;       wtile_store(tc, tid, cur, lds);
; #pragma unroll
;       for (int i = 0; i < 4; ++i) cur[i] = nxt[i];
;       tc = tn; t2 = t2n;
;     }
;   }
.LBB0_157:
	v_readlane_b32 s100, v255, 63
	s_nop 0
	s_cmp_lt_u32 s100, 4
	s_cbranch_scc0 .Lmy_prio_skip_0
	s_setprio 1

; DI int my_tid() { int t = tid_raw(); asm volatile("" : "+v"(t)); return t; }
; __global__ void __launch_bounds__(512, 2) fwd_megakernel(Params p) {
;     ...
;     p1_phase(p, layer, lds);
;     xcd_barrier(xb);
;     {
;       for (int g2 = blockIdx.x; g2 < 256; g2 += gridDim.x)
; #pragma unroll 1
;         for (int rr = 0; rr < 2; ++rr) attn_task(p, g2 & 7, 511 - ((g2 >> 3) * 16 + rr * 8 + (my_tid() >> 6)));
.LBB0_779:
	s_setprio 0
	s_or_b64 exec, exec, s[8:9]
	v_readlane_b32 s2, v254, 0
	v_readlane_b32 s3, v254, 1
	s_andn2_b64 vcc, exec, s[2:3]
	s_waitcnt lgkmcnt(0)
	v_cndmask_b32_e64 v0, 0, 1, s[2:3]
	v_cmp_ne_u32_e64 s[8:9], 1, v0
	s_mov_b32 s2, s74
	s_mov_b32 s3, s74
	v_writelane_b32 v255, s8, 44
	s_barrier
	s_nop 0
	v_writelane_b32 v255, s9, 45
	s_nop 0
	v_readlane_b32 s7, v255, 6
	s_cbranch_vccz .LBB0_785

; DI int my_tid() { int t = tid_raw(); asm volatile("" : "+v"(t)); return t; }
; DI void ln_phase(const Params& p, const u16* src, const float* g, const float* b, float* dstf, u16* dstb) {
;   const int lane = my_tid() & 63, wid = my_tid() >> 6;
;   const int stride = gridDim.x * 8;
;   int row = blockIdx.x * 8 + wid;
;   u32x2 raw[4], nxt[4];
;   f32x4 gv[4], bv[4];
; #pragma unroll
;   for (int i = 0; i < 4; ++i) { gv[i] = *(const f32x4*)(g + i * 256 + lane * 4); bv[i] = *(const f32x4*)(b + i * 256 + lane * 4); }
;   if (row < S) {
; #pragma unroll
;     for (int i = 0; i < 4; ++i) raw[i] = *(const u32x2*)(src + (size_t)row * D + i * 256 + lane * 4);
;   }
.LBB0_1109:
	s_setprio 0
	s_movk_i32 s59, 0x3c0
	s_movk_i32 s58, 0x3000
	s_or_b64 exec, exec, s[8:9]
	s_waitcnt lgkmcnt(0)
	s_barrier
	s_getreg_b32 s2, hwreg(HW_REG_HW_ID, 0, 6)
	s_lshl_b32 s2, s2, 2
	s_and_b32 s2, s2, 0xfc
	s_add_i32 s2, s2, 0x20040
	v_mov_b32_e32 v0, s2
	ds_read_b32 v0, v0
	s_lshl_b32 s92, s69, 10
	s_waitcnt lgkmcnt(0)
	v_readfirstlane_b32 s2, v0
	s_nop 1
	v_lshl_or_b32 v34, s2, 6, v214
	s_getreg_b32 s2, hwreg(HW_REG_HW_ID, 0, 6)
	s_lshl_b32 s2, s2, 2
	s_and_b32 s2, s2, 0xfc
	s_add_i32 s2, s2, 0x20040
	v_mov_b32_e32 v0, s2
	ds_read_b32 v0, v0
	s_waitcnt lgkmcnt(0)
	v_readfirstlane_b32 s2, v0
	s_nop 1
	v_lshl_or_b32 v0, s2, 6, v214
	v_readlane_b32 s2, v255, 12
	v_ashrrev_i32_e32 v36, 6, v0
	s_nop 0
	v_add_u32_e32 v32, s2, v36
	s_movk_i32 s2, 0x4000
	v_cmp_gt_i32_e32 vcc, s2, v32
	s_and_saveexec_b64 s[8:9], vcc
	s_cbranch_execz .LBB0_1114
	s_lshl_b64 s[2:3], s[92:93], 2
	v_readlane_b32 s36, v252, 18
	v_readlane_b32 s37, v252, 19
	s_add_u32 s22, s36, s2
	v_readlane_b32 s38, v252, 20
	s_addc_u32 s23, s37, s3
	v_lshlrev_b32_e32 v35, 2, v34
	v_readlane_b32 s39, v252, 21
	s_add_u32 s2, s38, s2
	v_and_b32_e32 v37, 0xfc, v35
	s_addc_u32 s3, s39, s3
	v_lshlrev_b32_e32 v28, 2, v37
	global_load_dwordx4 v[0:3], v28, s[22:23]
	global_load_dwordx4 v[4:7], v28, s[22:23] offset:1024
	global_load_dwordx4 v[8:11], v28, s[2:3]
	global_load_dwordx4 v[12:15], v28, s[2:3] offset:1024
	global_load_dwordx4 v[16:19], v28, s[22:23] offset:2048
	global_load_dwordx4 v[20:23], v28, s[22:23] offset:3072
	global_load_dwordx4 v[24:27], v28, s[2:3] offset:2048
	s_nop 0
	global_load_dwordx4 v[28:31], v28, s[2:3] offset:3072
	v_ashrrev_i32_e32 v33, 31, v32
	v_readlane_b32 s2, v254, 14
	v_lshlrev_b64 v[38:39], 11, v[32:33]
	v_readlane_b32 s3, v254, 15
	v_lshlrev_b32_e32 v64, 1, v37
	v_bfrev_b32_e32 v37, 0.5
	v_lshl_add_u64 v[40:41], s[2:3], 0, v[38:39]
	v_lshl_add_u64 v[40:41], v[40:41], 0, v[64:65]
	global_load_dwordx2 v[52:53], v[40:41], off
	global_load_dwordx2 v[50:51], v[40:41], off offset:512
	global_load_dwordx2 v[48:49], v[40:41], off offset:1024
	global_load_dwordx2 v[46:47], v[40:41], off offset:1536
	s_movk_i32 s2, 0x80
	v_bitop3_b32 v33, v35, s2, v37 bitop3:0x6c
	v_readlane_b32 s2, v255, 13
	v_bitop3_b32 v54, v35, 64, v37 bitop3:0x6c
	v_bitop3_b32 v55, v35, 32, v37 bitop3:0x6c
	v_add_u32_e32 v36, s2, v36
	v_bitop3_b32 v56, v35, 16, v37 bitop3:0x6c
	v_bitop3_b32 v57, v35, 8, v37 bitop3:0x6c
	v_bitop3_b32 v58, v35, 4, v37 bitop3:0x6c
	v_and_b32_e32 v34, 63, v34
	v_ashrrev_i32_e32 v37, 31, v36
	v_lshlrev_b32_e32 v64, 3, v34
	v_lshl_add_u64 v[34:35], s[90:91], 0, v[38:39]
	v_lshlrev_b64 v[36:37], 11, v[36:37]
	v_mov_b32_e32 v38, 0
	v_lshl_add_u64 v[36:37], s[90:91], 0, v[36:37]
	s_mov_b64 s[22:23], 0
	v_mov_b32_e32 v39, v38
	v_mov_b32_e32 v40, v38
	v_mov_b32_e32 v41, v38
	v_mov_b32_e32 v42, v38
	v_mov_b32_e32 v43, v38
	v_mov_b32_e32 v44, v38
	v_mov_b32_e32 v45, v38
	v_readlane_b32 s40, v252, 22
	v_readlane_b32 s41, v252, 23
	v_readlane_b32 s42, v252, 24
	v_readlane_b32 s43, v252, 25
	v_readlane_b32 s44, v252, 26
	v_readlane_b32 s45, v252, 27
	v_readlane_b32 s46, v252, 28
	v_readlane_b32 s47, v252, 29
	v_readlane_b32 s48, v252, 30
	v_readlane_b32 s49, v252, 31
	v_readlane_b32 s50, v252, 32
	v_readlane_b32 s51, v252, 33
	s_branch .LBB0_1112

; DI int my_tid() { int t = tid_raw(); asm volatile("" : "+v"(t)); return t; }
; DI void ln_phase(const Params& p, const u16* src, const float* g, const float* b, float* dstf, u16* dstb) {
;   const int lane = my_tid() & 63, wid = my_tid() >> 6;
;   const int stride = gridDim.x * 8;
;   int row = blockIdx.x * 8 + wid;
;   u32x2 raw[4], nxt[4];
;   f32x4 gv[4], bv[4];
; #pragma unroll
;   for (int i = 0; i < 4; ++i) { gv[i] = *(const f32x4*)(g + i * 256 + lane * 4); bv[i] = *(const f32x4*)(b + i * 256 + lane * 4); }
;   if (row < S) {
; #pragma unroll
;     for (int i = 0; i < 4; ++i) raw[i] = *(const u32x2*)(src + (size_t)row * D + i * 256 + lane * 4);
;   }
.LBB0_1322:
	s_setprio 0
	s_or_b64 exec, exec, s[8:9]
	s_waitcnt lgkmcnt(0)
	s_barrier
	s_getreg_b32 s2, hwreg(HW_REG_HW_ID, 0, 6)
	s_lshl_b32 s2, s2, 2
	s_and_b32 s2, s2, 0xfc
	s_add_i32 s2, s2, 0x20040
	v_mov_b32_e32 v0, s2
	ds_read_b32 v0, v0
	s_waitcnt lgkmcnt(0)
	v_readfirstlane_b32 s2, v0
	s_nop 1
	v_lshl_or_b32 v38, s2, 6, v214
	s_getreg_b32 s2, hwreg(HW_REG_HW_ID, 0, 6)
	s_lshl_b32 s2, s2, 2
	s_and_b32 s2, s2, 0xfc
	s_add_i32 s2, s2, 0x20040
	v_mov_b32_e32 v0, s2
	ds_read_b32 v0, v0
	s_waitcnt lgkmcnt(0)
	v_readfirstlane_b32 s2, v0
	s_nop 1
	v_lshl_or_b32 v0, s2, 6, v214
	v_readlane_b32 s2, v255, 12
	v_ashrrev_i32_e32 v39, 6, v0
	s_nop 0
	v_add_u32_e32 v36, s2, v39
	s_movk_i32 s2, 0x4000
	v_cmp_gt_i32_e32 vcc, s2, v36
	s_and_saveexec_b64 s[8:9], vcc
	s_cbranch_execz .LBB0_1343
	s_lshl_b64 s[2:3], s[92:93], 2
	s_add_u32 s22, s84, s2
	s_addc_u32 s23, s85, s3
	v_lshlrev_b32_e32 v42, 2, v38
	s_add_u32 s2, s86, s2
	v_and_b32_e32 v34, 0xfc, v42
	s_addc_u32 s3, s87, s3
	v_lshlrev_b32_e32 v28, 2, v34
	global_load_dwordx4 v[0:3], v28, s[22:23]
	global_load_dwordx4 v[4:7], v28, s[22:23] offset:1024
	global_load_dwordx4 v[8:11], v28, s[2:3]
	global_load_dwordx4 v[12:15], v28, s[2:3] offset:1024
	global_load_dwordx4 v[16:19], v28, s[22:23] offset:2048
	global_load_dwordx4 v[20:23], v28, s[22:23] offset:3072
	global_load_dwordx4 v[24:27], v28, s[2:3] offset:2048
	s_nop 0
	global_load_dwordx4 v[28:31], v28, s[2:3] offset:3072
	v_ashrrev_i32_e32 v37, 31, v36
	v_readlane_b32 s2, v254, 20
	v_lshlrev_b64 v[40:41], 11, v[36:37]
	v_readlane_b32 s3, v254, 21
	v_lshlrev_b32_e32 v64, 1, v34
	s_movk_i32 s7, 0x80
	v_lshl_add_u64 v[32:33], s[2:3], 0, v[40:41]
	v_lshl_add_u64 v[32:33], v[32:33], 0, v[64:65]
	global_load_dwordx2 v[54:55], v[32:33], off
	global_load_dwordx2 v[52:53], v[32:33], off offset:512
	global_load_dwordx2 v[34:35], v[32:33], off offset:1024
	s_nop 0
	global_load_dwordx2 v[32:33], v[32:33], off offset:1536
	s_and_b64 s[2:3], s[46:47], exec
	v_bfrev_b32_e32 v43, 0.5
	v_readlane_b32 s2, v254, 22
	v_bitop3_b32 v70, v42, s7, v43 bitop3:0x6c
	v_readlane_b32 s7, v255, 13
	v_readlane_b32 s3, v254, 23
	v_readlane_b32 s36, v255, 29
	v_bitop3_b32 v71, v42, 64, v43 bitop3:0x6c
	v_bitop3_b32 v72, v42, 32, v43 bitop3:0x6c
	v_bitop3_b32 v73, v42, 16, v43 bitop3:0x6c
	v_bitop3_b32 v74, v42, 8, v43 bitop3:0x6c
	v_bitop3_b32 v75, v42, 4, v43 bitop3:0x6c
	v_and_b32_e32 v44, 63, v38
	v_add_u32_e32 v38, s7, v39
	v_lshlrev_b64 v[42:43], 12, v[36:37]
	s_cselect_b32 s3, s3, 0
	s_cselect_b32 s2, s2, 0
	v_readlane_b32 s37, v255, 30
	v_ashrrev_i32_e32 v39, 31, v38
	v_lshl_or_b32 v42, v44, 4, v42
	s_cmp_lg_u64 s[36:37], 0
	v_lshlrev_b32_e32 v64, 3, v44
	v_lshlrev_b64 v[38:39], 11, v[38:39]
	v_lshl_add_u64 v[40:41], s[2:3], 0, v[40:41]
	v_lshl_add_u64 v[42:43], s[36:37], 0, v[42:43]
	s_mov_b64 s[2:3], 0x800
	v_mov_b32_e32 v44, 0
	s_mov_b64 s[22:23], 0
	s_cselect_b64 s[28:29], -1, 0
	v_lshl_add_u64 v[38:39], s[90:91], 0, v[38:39]
	v_lshl_add_u64 v[42:43], v[42:43], 0, s[2:3]
	v_mov_b32_e32 v45, v44
	v_mov_b32_e32 v46, v44
	v_mov_b32_e32 v47, v44
	v_mov_b32_e32 v48, v44
	v_mov_b32_e32 v49, v44
	v_mov_b32_e32 v50, v44
	v_mov_b32_e32 v51, v44
	s_branch .LBB0_1325
